# P2 interleave selected by vcu bit 1
# speedup vs baseline: 1.0004x; 1.0004x over previous
; __global__ void __launch_bounds__(NWAVES * 64, 2) mega_fwd(Args args) {
;     ...
;     if (IN(2)) {
;         const float d1 = wave_sum(lq1[lane] * lk1[lane]), d2 = wave_sum(lq2[lane] * lk2[lane]);
;         const float lam = expf(d1) - expf(d2) + 0.2f;
;         const att::SideJob SJ{w_out, w_up, w_dn, g_mlp, WOUT, WUP, WDN, vcu, 256, (G == 256) ? 36 : 0};
;         for (int u = vcu; u < BATCH * NHEAD * 16; u += G) {
;             const int bh = u >> 4, qb = u & 15;
;             datt::diff_unit2<8>(PROJ, KBI, VBI, out, MIX, subg, lam, bh >> 3, bh & 7, qb, (char*)lds + RING_OFF, SJ, (const unsigned*)(ctl + CW_P1D), (G == 256 && N_LAUNCHES != PER_PHASE) ? 256u : 0u);
;         }
;         for (int u = vcu; u < BATCH * NHEAD * 16; u += G) {
;             const int bh = u >> 4, rg = u & 15;
;             att::na_unit<0>(PROJ, MIX, relb, bh >> 3, bh & 7, rg, (char*)lds + RING_OFF);
;         }
.LBB0_395:
	v_readlane_b32 s4, v242, 6
	v_readlane_b32 s5, v242, 7
	s_cmp_lt_i32 s4, 3
	s_cselect_b64 s[0:1], -1, 0
	s_cmp_gt_i32 s5, 2
	s_cselect_b64 s[2:3], -1, 0
	s_and_b64 s[0:1], s[0:1], s[2:3]
	s_andn2_b64 vcc, exec, s[0:1]
	s_cbranch_vccnz .LBB0_628
	v_writelane_b32 v242, 0, 62
	s_bitcmp1_b32 s76, 1
	s_cbranch_scc1 .Lp2_nafirst
